# N2 norm_rows: one-dword-per-cache-line touch of the next row (L2 warm-up), counted waits adjusted (on top of v45)
# baseline (speedup 1.0000x reference)
; #define p (kparams())
; __device__ __forceinline__ void norm_rows(const int wv_, KPR p, int l, int src_layer, const float* gvec, int part_shift, int part_scale, bool copy_ctx) {
;     ...
;   for (int row = blockIdx.x * 8 + wid; row < T; row += gridDim.x * 8) {
;     const float* x = xrow_ptr(p, src_layer, row);
;     const float* mw = modl + (size_t)row_who(row) * 12288;
;     f32x4 v[8]; float ss = 0.f;
; #pragma unroll
;     for (int j = 0; j < 8; ++j) { v[j] = *(const f32x4*)(x + lane * 4 + 256 * j); ss += v[j][0] * v[j][0] + v[j][1] * v[j][1] + v[j][2] * v[j][2] + v[j][3] * v[j][3]; }
;     const float rstd = rsqrtf(wave_sum(ss) * (1.f / D) + 1e-6f);
.LBB0_1103:
	s_or_b64 exec, exec, s[20:21]
	v_add_u32_e32 v228, 0x800, v4
	v_min_i32_e32 v228, 0x3fff, v228
	v_sub_u32_e32 v228, v228, v4
	v_mov_b32_e32 v229, v2
	v_lshlrev_b64 v[228:229], 13, v[228:229]
	v_ashrrev_i32_e32 v5, 31, v4
	v_lshlrev_b64 v[4:5], 13, v[4:5]
	v_lshl_add_u64 v[4:5], v[6:7], 0, v[4:5]
	v_mov_b32_e32 v49, v2
	v_lshl_add_u64 v[4:5], v[4:5], 0, v[48:49]
	v_lshl_add_u64 v[228:229], v[4:5], 0, v[228:229]
	v_mul_u32_u24_e32 v230, 7, v48
	v_mov_b32_e32 v231, v2
	v_lshl_add_u64 v[228:229], v[228:229], 0, v[230:231]
	global_load_dwordx4 v[32:35], v[4:5], off
	global_load_dwordx4 v[28:31], v[4:5], off offset:1024
	global_load_dwordx4 v[24:27], v[4:5], off offset:2048
	global_load_dwordx4 v[20:23], v[4:5], off offset:3072
	v_add_co_u32_e32 v4, vcc, s52, v4
	s_mov_b64 s[20:21], 0x6000
	s_nop 0
	v_addc_co_u32_e32 v5, vcc, 0, v5, vcc
	global_load_dwordx4 v[16:19], v[4:5], off
	global_load_dwordx4 v[12:15], v[4:5], off offset:1024
	global_load_dwordx4 v[232:235], v[4:5], off offset:2048
	global_load_dwordx4 v[236:239], v[4:5], off offset:3072
	v_lshl_add_u64 v[66:67], s[12:13], 0, v[64:65]
	v_lshl_add_u64 v[68:69], v[66:67], 0, s[20:21]
	s_mov_b64 s[20:21], 0x8000
	v_lshl_add_u64 v[66:67], v[66:67], 0, s[20:21]
	v_lshl_add_u64 v[74:75], v[68:69], 0, v[48:49]
	v_lshl_add_u64 v[78:79], v[66:67], 0, v[48:49]
	s_mov_b64 s[22:23], 0x1000
	v_lshl_add_u64 v[224:225], v[78:79], 0, s[22:23]
	v_lshl_add_u64 v[226:227], v[74:75], 0, s[22:23]
	global_load_dwordx4 v[120:123], v[78:79], off
	global_load_dwordx4 v[190:193], v[74:75], off
	global_load_dwordx4 v[124:127], v[78:79], off offset:1024
	global_load_dwordx4 v[194:197], v[74:75], off offset:1024
	global_load_dwordx4 v[128:131], v[78:79], off offset:2048
	global_load_dwordx4 v[198:201], v[74:75], off offset:2048
	global_load_dwordx4 v[132:135], v[78:79], off offset:3072
	global_load_dwordx4 v[202:205], v[74:75], off offset:3072
	global_load_dwordx4 v[136:139], v[224:225], off
	global_load_dwordx4 v[206:209], v[226:227], off
	global_load_dwordx4 v[140:143], v[224:225], off offset:1024
	global_load_dwordx4 v[210:213], v[226:227], off offset:1024
	global_load_dwordx4 v[144:147], v[224:225], off offset:2048
	global_load_dwordx4 v[214:217], v[226:227], off offset:2048
	global_load_dwordx4 v[148:151], v[224:225], off offset:3072
	global_load_dwordx4 v[218:221], v[226:227], off offset:3072
	global_load_dword v240, v[228:229], off
	v_mov_b32_e32 v51, v2
	v_mov_b32_e32 v53, v2
	v_mov_b32_e32 v55, v2
	v_mov_b32_e32 v57, v2
	v_mov_b32_e32 v59, v2
	v_mov_b32_e32 v61, v2
	v_mov_b32_e32 v63, v2
	s_waitcnt vmcnt(24)
	v_mul_f32_e32 v1, v33, v33
	s_waitcnt vmcnt(23)
	v_mul_f32_e32 v3, v29, v29
	v_fmac_f32_e32 v1, v32, v32
	v_fmac_f32_e32 v3, v28, v28
	v_fmac_f32_e32 v1, v34, v34
	v_fmac_f32_e32 v3, v30, v30
	v_fmac_f32_e32 v1, v35, v35
	v_fmac_f32_e32 v3, v31, v31
	v_add_f32_e32 v1, v1, v3
	s_waitcnt vmcnt(22)
	v_mul_f32_e32 v3, v25, v25
	v_fmac_f32_e32 v3, v24, v24
	v_fmac_f32_e32 v3, v26, v26
	v_fmac_f32_e32 v3, v27, v27
	v_add_f32_e32 v1, v1, v3
	s_waitcnt vmcnt(21)
	v_mul_f32_e32 v3, v21, v21
	s_waitcnt vmcnt(20)
	v_mov_b32_e32 v8, v17
	s_waitcnt vmcnt(19)
	v_mov_b32_e32 v9, v13
	v_fmac_f32_e32 v3, v20, v20
	v_mov_b32_e32 v6, v16
	v_mov_b32_e32 v7, v12
	v_pk_mul_f32 v[8:9], v[8:9], v[8:9]
	v_fmac_f32_e32 v3, v22, v22
	v_pk_fma_f32 v[6:7], v[6:7], v[6:7], v[8:9]
	v_mov_b32_e32 v8, v18
	v_mov_b32_e32 v9, v14
	v_fmac_f32_e32 v3, v23, v23
	v_pk_fma_f32 v[6:7], v[8:9], v[8:9], v[6:7]
	v_mov_b32_e32 v8, v19
	v_mov_b32_e32 v9, v15
	v_add_f32_e32 v1, v1, v3
	v_pk_fma_f32 v[6:7], v[8:9], v[8:9], v[6:7]
	s_nop 0
	v_add_f32_e32 v1, v1, v6
	v_add_f32_e32 v1, v1, v7
	s_waitcnt vmcnt(18)
	v_mov_b32_e32 v68, v233
	s_waitcnt vmcnt(17)
	v_mov_b32_e32 v69, v237
	v_mov_b32_e32 v66, v232
	v_mov_b32_e32 v67, v236
	v_pk_mul_f32 v[68:69], v[68:69], v[68:69]
	v_pk_fma_f32 v[66:67], v[66:67], v[66:67], v[68:69]
	v_mov_b32_e32 v68, v234
	v_mov_b32_e32 v69, v238
	v_pk_fma_f32 v[66:67], v[68:69], v[68:69], v[66:67]
	v_mov_b32_e32 v68, v235
	v_mov_b32_e32 v69, v239
	v_pk_fma_f32 v[66:67], v[68:69], v[68:69], v[66:67]
	s_nop 0
	v_add_f32_e32 v1, v1, v66
	v_add_f32_e32 v1, v1, v67
	ds_bpermute_b32 v3, v170, v1
	s_waitcnt lgkmcnt(0)
	v_add_f32_e32 v1, v1, v3
	ds_bpermute_b32 v3, v171, v1
	s_waitcnt lgkmcnt(0)
	v_add_f32_e32 v1, v1, v3
	ds_bpermute_b32 v3, v172, v1
	s_waitcnt lgkmcnt(0)
	v_add_f32_e32 v1, v1, v3
	ds_bpermute_b32 v3, v173, v1
	s_waitcnt lgkmcnt(0)
	v_add_f32_e32 v1, v1, v3
	ds_bpermute_b32 v3, v174, v1
	s_waitcnt lgkmcnt(0)
	v_add_f32_e32 v1, v1, v3
	ds_bpermute_b32 v3, v175, v1
	s_waitcnt lgkmcnt(0)
; __device__ __forceinline__ unsigned pk2(float lo, float hi) { f32x2n v = {lo, hi}; bf16x2n b = __builtin_convertvector(v, bf16x2n); return __builtin_bit_cast(unsigned, b); }
; #define p (kparams())
; __device__ __forceinline__ void norm_rows(const int wv_, KPR p, int l, int src_layer, const float* gvec, int part_shift, int part_scale, bool copy_ctx) {
;     ...
;     const float rstd = rsqrtf(wave_sum(ss) * (1.f / D) + 1e-6f);
;     if (copy_ctx && row_who(row) == 4) { float* xd = xrow_dst(p, row);
; #pragma unroll
;       for (int j = 0; j < 8; ++j) *(f32x4*)(xd + lane * 4 + 256 * j) = v[j]; }
; #pragma unroll
;     for (int j = 0; j < 8; ++j) { const int c = lane * 4 + 256 * j;
;       const f32x4 g = *(const f32x4*)(gvec + c), sh = *(const f32x4*)(mw + part_shift * 2048 + c), sc = *(const f32x4*)(mw + part_scale * 2048 + c);
;       f32x4 o;
; #pragma unroll
;       for (int e = 0; e < 4; ++e) o[e] = v[j][e] * rstd * g[e] * (1.f + sc[e]) + sh[e];
;       u32x2 w; w.x = pk2(o[0], o[1]); w.y = pk2(o[2], o[3]);
;       *(u32x2*)(H + (size_t)row * D + c) = w; }
	v_add_f32_e32 v1, v1, v3
	v_fmamk_f32 v1, v1, 0x3a000000, v152
	v_cmp_gt_f32_e32 vcc, s96, v1
	v_mul_f32_e32 v3, 0x4b800000, v1
	s_nop 0
	v_cndmask_b32_e32 v1, v1, v3, vcc
	v_rsq_f32_e32 v1, v1
	s_nop 0
	v_mul_f32_e32 v3, 0x45800000, v1
	v_cndmask_b32_e32 v64, v1, v3, vcc
	v_pk_mul_f32 v[32:33], v[32:33], v[64:65] op_sel_hi:[1,0]
	v_pk_mul_f32 v[34:35], v[34:35], v[64:65] op_sel_hi:[1,0]
	v_pk_mul_f32 v[28:29], v[28:29], v[64:65] op_sel_hi:[1,0]
	v_pk_mul_f32 v[30:31], v[30:31], v[64:65] op_sel_hi:[1,0]
	v_pk_mul_f32 v[24:25], v[24:25], v[64:65] op_sel_hi:[1,0]
	v_pk_mul_f32 v[26:27], v[26:27], v[64:65] op_sel_hi:[1,0]
	v_pk_mul_f32 v[20:21], v[20:21], v[64:65] op_sel_hi:[1,0]
	v_pk_mul_f32 v[22:23], v[22:23], v[64:65] op_sel_hi:[1,0]
	v_pk_mul_f32 v[16:17], v[16:17], v[64:65] op_sel_hi:[1,0]
	v_pk_mul_f32 v[18:19], v[18:19], v[64:65] op_sel_hi:[1,0]
	v_pk_mul_f32 v[12:13], v[12:13], v[64:65] op_sel_hi:[1,0]
	v_pk_mul_f32 v[14:15], v[14:15], v[64:65] op_sel_hi:[1,0]
	v_pk_mul_f32 v[232:233], v[232:233], v[64:65] op_sel_hi:[1,0]
	v_pk_mul_f32 v[234:235], v[234:235], v[64:65] op_sel_hi:[1,0]
	v_pk_mul_f32 v[236:237], v[236:237], v[64:65] op_sel_hi:[1,0]
	v_pk_mul_f32 v[238:239], v[238:239], v[64:65] op_sel_hi:[1,0]
	v_ashrrev_i32_e32 v1, 31, v0
	v_lshlrev_b64 v[82:83], 12, v[0:1]
	v_lshl_add_u64 v[70:71], v[46:47], 0, v[82:83]
	v_add_u32_e32 v0, s73, v0
	v_cmp_lt_i32_e32 vcc, s38, v0
	s_or_b64 s[18:19], vcc, s[18:19]
	s_waitcnt vmcnt(15)
	v_pk_mul_f32 v[32:33], v[88:89], v[32:33]
	v_pk_mul_f32 v[34:35], v[90:91], v[34:35]
	v_pk_add_f32 v[228:229], v[120:121], 1.0 op_sel_hi:[1,0]
	v_pk_add_f32 v[230:231], v[122:123], 1.0 op_sel_hi:[1,0]
	v_pk_fma_f32 v[32:33], v[228:229], v[32:33], v[190:191]
	v_pk_fma_f32 v[34:35], v[230:231], v[34:35], v[192:193]
	v_cvt_pk_bf16_f32 v32, v32, v33
	v_cvt_pk_bf16_f32 v33, v34, v35
	global_store_dwordx2 v[70:71], v[32:33], off
	s_waitcnt vmcnt(14)
	v_pk_mul_f32 v[28:29], v[92:93], v[28:29]
	v_pk_mul_f32 v[30:31], v[94:95], v[30:31]
	v_pk_add_f32 v[228:229], v[124:125], 1.0 op_sel_hi:[1,0]
	v_pk_add_f32 v[230:231], v[126:127], 1.0 op_sel_hi:[1,0]
	v_pk_fma_f32 v[28:29], v[228:229], v[28:29], v[194:195]
	v_pk_fma_f32 v[30:31], v[230:231], v[30:31], v[196:197]
	v_cvt_pk_bf16_f32 v28, v28, v29
	v_cvt_pk_bf16_f32 v29, v30, v31
	global_store_dwordx2 v[70:71], v[28:29], off offset:512
	s_waitcnt vmcnt(13)
	v_pk_mul_f32 v[24:25], v[96:97], v[24:25]
	v_pk_mul_f32 v[26:27], v[98:99], v[26:27]
	v_pk_add_f32 v[228:229], v[128:129], 1.0 op_sel_hi:[1,0]
	v_pk_add_f32 v[230:231], v[130:131], 1.0 op_sel_hi:[1,0]
	v_pk_fma_f32 v[24:25], v[228:229], v[24:25], v[198:199]
	v_pk_fma_f32 v[26:27], v[230:231], v[26:27], v[200:201]
	v_cvt_pk_bf16_f32 v24, v24, v25
	v_cvt_pk_bf16_f32 v25, v26, v27
	global_store_dwordx2 v[70:71], v[24:25], off offset:1024
	s_waitcnt vmcnt(12)
	v_pk_mul_f32 v[20:21], v[100:101], v[20:21]
	v_pk_mul_f32 v[22:23], v[102:103], v[22:23]
	v_pk_add_f32 v[228:229], v[132:133], 1.0 op_sel_hi:[1,0]
	v_pk_add_f32 v[230:231], v[134:135], 1.0 op_sel_hi:[1,0]
	v_pk_fma_f32 v[20:21], v[228:229], v[20:21], v[202:203]
	v_pk_fma_f32 v[22:23], v[230:231], v[22:23], v[204:205]
	v_cvt_pk_bf16_f32 v20, v20, v21
	v_cvt_pk_bf16_f32 v21, v22, v23
	global_store_dwordx2 v[70:71], v[20:21], off offset:1536
	s_waitcnt vmcnt(11)
	v_pk_mul_f32 v[16:17], v[104:105], v[16:17]
	v_pk_mul_f32 v[18:19], v[106:107], v[18:19]
	v_pk_add_f32 v[228:229], v[136:137], 1.0 op_sel_hi:[1,0]
	v_pk_add_f32 v[230:231], v[138:139], 1.0 op_sel_hi:[1,0]
	v_pk_fma_f32 v[16:17], v[228:229], v[16:17], v[206:207]
	v_pk_fma_f32 v[18:19], v[230:231], v[18:19], v[208:209]
	v_cvt_pk_bf16_f32 v16, v16, v17
	v_cvt_pk_bf16_f32 v17, v18, v19
	global_store_dwordx2 v[70:71], v[16:17], off offset:2048
	s_waitcnt vmcnt(10)
	v_pk_mul_f32 v[12:13], v[108:109], v[12:13]
	v_pk_mul_f32 v[14:15], v[110:111], v[14:15]
	v_pk_add_f32 v[228:229], v[140:141], 1.0 op_sel_hi:[1,0]
	v_pk_add_f32 v[230:231], v[142:143], 1.0 op_sel_hi:[1,0]
	v_pk_fma_f32 v[12:13], v[228:229], v[12:13], v[210:211]
	v_pk_fma_f32 v[14:15], v[230:231], v[14:15], v[212:213]
	v_cvt_pk_bf16_f32 v12, v12, v13
	v_cvt_pk_bf16_f32 v13, v14, v15
	global_store_dwordx2 v[70:71], v[12:13], off offset:2560
	s_waitcnt vmcnt(9)
	v_pk_mul_f32 v[232:233], v[112:113], v[232:233]
	v_pk_mul_f32 v[234:235], v[114:115], v[234:235]
	v_pk_add_f32 v[228:229], v[144:145], 1.0 op_sel_hi:[1,0]
	v_pk_add_f32 v[230:231], v[146:147], 1.0 op_sel_hi:[1,0]
	v_pk_fma_f32 v[232:233], v[228:229], v[232:233], v[214:215]
	v_pk_fma_f32 v[234:235], v[230:231], v[234:235], v[216:217]
	v_cvt_pk_bf16_f32 v232, v232, v233
	v_cvt_pk_bf16_f32 v233, v234, v235
	global_store_dwordx2 v[70:71], v[232:233], off offset:3072
	s_waitcnt vmcnt(8)
	v_pk_mul_f32 v[236:237], v[116:117], v[236:237]
	v_pk_mul_f32 v[238:239], v[118:119], v[238:239]
	v_pk_add_f32 v[228:229], v[148:149], 1.0 op_sel_hi:[1,0]
	v_pk_add_f32 v[230:231], v[150:151], 1.0 op_sel_hi:[1,0]
	v_pk_fma_f32 v[236:237], v[228:229], v[236:237], v[218:219]
	v_pk_fma_f32 v[238:239], v[230:231], v[238:239], v[220:221]
	v_cvt_pk_bf16_f32 v236, v236, v237
	v_cvt_pk_bf16_f32 v237, v238, v239
	global_store_dwordx2 v[70:71], v[236:237], off offset:3584
	s_andn2_b64 exec, exec, s[18:19]
	s_cbranch_execz .LBB0_1108
